# A2 loop: next K/V tile staged by direct global->LDS loads (global_load_lds_dwordx4, permuted per-lane source addresses) instead of VGPR staging + ds_write_b128
# speedup vs baseline: 1.0062x; 1.0062x over previous
; __device__ __forceinline__ int v_st(int k, int c) { const int kk = (k & ~0xC) | ((k & 4) << 1) | ((k & 8) >> 1); return ((kk >> 3) * 4 + (c >> 5)) * 512 + ((kk & 7) * 32 + (c & 31)) * 2; }
; __device__ __forceinline__ int v_rd_base(int lane) { return ((lane & 3) << 3) | (((lane >> 2) & 3) << 6) | (((lane >> 4) & 1) << 5) | (((lane >> 5) & 1) << 8); }
; #define SLOAD2(k0) do { vs0 = *reinterpret_cast<const bf16x8*>(&Vh[(long)((k0) + sr) * ldv + sc]); vs1 = *reinterpret_cast<const bf16x8*>(&Vh[(long)((k0) + 32 + sr) * ldv + sc]); \
;     ks0 = *reinterpret_cast<const bf16x8*>(&Kh[(long)((k0) + sr) * ldk + sc]); ks1 = *reinterpret_cast<const bf16x8*>(&Kh[(long)((k0) + 32 + sr) * ldk + sc]); } while (0)
; #define SWRITE2(b) do { *(bf16x8*)(V_lds + (b) * SHM_V + vst0) = vs0; *(bf16x8*)(V_lds + (b) * SHM_V + vst1) = vs1; \
;     *(bf16x8*)(K_lds + (b) * SHM_K + KSWZ(sr, sc * 2)) = ks0; *(bf16x8*)(K_lds + (b) * SHM_K + KSWZ(32 + sr, sc * 2)) = ks1; } while (0)
; __device__ __forceinline__ void attn_unit_A2(const bf16_t* __restrict__ Qb, int ldq, const bf16_t* __restrict__ Kh, int ldk, const bf16_t* __restrict__ Vh, int ldv, int nkeys, int q0, ...
;     ...
;   __syncthreads();
;   for (int i = tid; i < TBLN; i += 512) tbl_l[i] = tblg[i];
;   { const bf16_t* Qw = Qb + (long)(wid * QBLK + r32) * ldq + hi * 8;
; #pragma unroll
;     for (int i = 0; i < 8; ++i) *reinterpret_cast<bf16x8*>(qls + i * 1024) = *reinterpret_cast<const bf16x8*>(Qw + i * 16); }
;   float m0 = -1e30f, m1 = -1e30f, l0 = 0.f, l1 = 0.f; f32x16 oa[4] = {}, ob[4] = {};
;   const int sr = tid >> 4, sc = (tid & 15) * 8, vst0 = v_st(sr, sc), vst1 = v_st(32 + sr, sc);
;   const int vb0 = (int)(uintptr_t)V_lds + v_rd_base(lane);
;   const int qlane = q0 + wid * QBLK + r32;
;   bf16x8 vs0, vs1, ks0, ks1;
;     ...
;   const int NT = nkeys / KVBLK;
;   const int kbA = (int)(uintptr_t)K_lds + r32 * 256 + (((r32 & 15) << 4) ^ (hi << 4)), qaA = (int)(uintptr_t)qls;
;   SLOAD2(0); asm volatile("s_waitcnt vmcnt(0)" ::: "memory"); SWRITE2(0); __syncthreads();
.LBB0_334:
	s_or_b64 exec, exec, s[4:5]
	s_lshl_b32 s4, s57, 8
	s_and_b32 s7, s4, 0x2000
	s_lshl_b32 s4, s59, 3
	s_ashr_i32 s23, s59, 3
	s_and_b32 s4, s4, 32
	s_add_i32 s4, s4, s23
	s_lshl_b32 s6, s20, 8
	s_lshl_b32 s20, s4, 8
	s_ashr_i32 s21, s20, 31
	s_mul_i32 s4, s4, 0x280000
	s_mul_hi_i32 s5, s20, 0x2800
	s_add_u32 s4, s24, s4
	s_addc_u32 s5, s25, s5
	s_lshl_b32 s10, s22, 7
	s_lshl_b32 s8, s22, 8
	v_ashrrev_i32_e32 v3, 6, v2
	s_add_u32 s4, s4, s8
	s_addc_u32 s5, s5, 0
	v_and_b32_e32 v46, 31, v6
	v_lshlrev_b32_e32 v196, 5, v3
	v_or_b32_e32 v0, v196, v46
	v_mov_b64_e32 v[4:5], s[4:5]
	v_mad_i64_i32 v[4:5], s[4:5], v0, s55, v[4:5]
	v_and_b32_e32 v9, 63, v6
	s_add_u32 s4, s26, s8
	v_lshrrev_b32_e32 v47, 5, v9
	s_addc_u32 s5, s27, 0
	v_lshlrev_b32_e32 v0, 4, v47
	s_add_u32 s8, s45, s8
	v_lshl_add_u64 v[4:5], v[4:5], 0, v[0:1]
	s_addc_u32 s9, s46, 0
	v_lshlrev_b32_e32 v49, 3, v6
	global_load_dwordx4 v[10:13], v[4:5], off
	global_load_dwordx4 v[14:17], v[4:5], off offset:32
	global_load_dwordx4 v[18:21], v[4:5], off offset:64
	global_load_dwordx4 v[22:25], v[4:5], off offset:96
	global_load_dwordx4 v[26:29], v[4:5], off offset:128
	global_load_dwordx4 v[30:33], v[4:5], off offset:160
	global_load_dwordx4 v[34:37], v[4:5], off offset:192
	global_load_dwordx4 v[38:41], v[4:5], off offset:224
	v_ashrrev_i32_e32 v48, 4, v2
	v_and_b32_e32 v4, 0x78, v49
	v_mov_b64_e32 v[42:43], s[8:9]
	v_lshlrev_b32_e32 v4, 1, v4
	v_add_u32_e32 v50, 32, v48
	v_mad_i64_i32 v[44:45], s[8:9], v48, s55, v[42:43]
	v_mov_b32_e32 v5, v1
	v_lshl_add_u64 v[44:45], v[44:45], 0, v[4:5]
	v_mad_i64_i32 v[42:43], s[8:9], v50, s55, v[42:43]
	global_load_dwordx4 v[176:179], v[44:45], off
	v_lshl_add_u64 v[42:43], v[42:43], 0, v[4:5]
	global_load_dwordx4 v[180:183], v[42:43], off
	v_mov_b64_e32 v[42:43], s[4:5]
	v_mad_i64_i32 v[44:45], s[4:5], v48, s55, v[42:43]
	v_lshl_add_u64 v[44:45], v[44:45], 0, v[4:5]
	global_load_dwordx4 v[184:187], v[44:45], off
	v_mad_i64_i32 v[42:43], s[4:5], v50, s55, v[42:43]
	v_lshl_add_u64 v[42:43], v[42:43], 0, v[4:5]
	global_load_dwordx4 v[188:191], v[42:43], off
	s_waitcnt vmcnt(13)
	v_mul_f32_e32 v197, 0x3fb8aa3b, v7
	s_waitcnt vmcnt(12)
	v_mul_f32_e32 v207, 0x3fb8aa3b, v8
	v_lshlrev_b32_e32 v3, 13, v3
	v_lshlrev_b32_e32 v7, 4, v9
	v_and_b32_e32 v8, 0xfffff0, v48
	v_lshlrev_b32_e32 v42, 1, v48
	v_readlane_b32 s4, v254, 58
	v_lshrrev_b32_e32 v43, 1, v48
	v_bfe_u32 v44, v49, 5, 2
	v_add3_u32 v208, s4, v3, v7
	v_and_or_b32 v3, v48, 8, v8
	v_and_b32_e32 v45, 3, v48
	v_lshrrev_b32_e32 v3, 1, v3
	v_and_or_b32 v8, v48, 4, v45
	v_or_b32_e32 v3, v3, v44
	v_and_b32_e32 v5, 0x3fffffc0, v2
	v_lshlrev_b32_e32 v8, 6, v8
	v_and_b32_e32 v42, 48, v4
	v_lshlrev_b32_e32 v3, 9, v3
	s_add_i32 s37, 0, 0x14000
	v_or3_b32 v209, v3, v8, v42
	v_lshl_add_u32 v201, v5, 2, s37
	v_and_b32_e32 v3, 0xfffff0, v50
	v_lshlrev_b32_e32 v5, 1, v50
	v_and_or_b32 v3, v50, 8, v3
	v_lshrrev_b32_e32 v3, 1, v3
	v_or_b32_e32 v3, v3, v44
	v_lshlrev_b32_e32 v3, 9, v3
	v_or3_b32 v210, v3, v8, v42
	v_and_b32_e32 v2, 0xf0, v2
	s_add_i32 s44, 0, 0x8000
	v_and_b32_e32 v8, 0xc0, v7
	v_lshlrev_b32_e32 v7, 1, v9
	s_cmp_lg_u32 s44, -1
	s_cselect_b32 s4, s44, 0
	s_add_i32 s60, s20, 0x4ff
	s_waitcnt vmcnt(11)
	ds_write_b128 v208, v[10:13]
	s_waitcnt vmcnt(10)
	ds_write_b128 v208, v[14:17] offset:1024
	s_waitcnt vmcnt(9)
	ds_write_b128 v208, v[18:21] offset:2048
	s_waitcnt vmcnt(8)
	ds_write_b128 v208, v[22:25] offset:3072
	s_waitcnt vmcnt(7)
	ds_write_b128 v208, v[26:29] offset:4096
	s_waitcnt vmcnt(6)
	ds_write_b128 v208, v[30:33] offset:5120
	s_waitcnt vmcnt(5)
	ds_write_b128 v208, v[34:37] offset:6144
	s_waitcnt vmcnt(4)
	ds_write_b128 v208, v[38:41] offset:7168
	v_add_u32_e32 v12, 0, v209
	s_waitcnt vmcnt(0)
	v_and_b32_e32 v11, 15, v6
	v_bitop3_b32 v6, v47, v6, 15 bitop3:0x78
	v_and_b32_e32 v10, 32, v7
	v_lshlrev_b32_e32 v7, 8, v46
	v_lshlrev_b32_e32 v6, 4, v6
	v_lshlrev_b32_e32 v3, 3, v9
	v_add3_u32 v211, v7, s4, v6
	v_mad_i64_i32 v[6:7], s[4:5], v48, s55, 0
	s_waitcnt vmcnt(3)
	ds_write_b128 v12, v[176:179]
	v_add_u32_e32 v12, 0, v210
	s_waitcnt vmcnt(2)
	ds_write_b128 v12, v[180:183]
	v_lshlrev_b32_e32 v12, 8, v48
	v_bitop3_b32 v212, v4, v12, v2 bitop3:0xde
	v_add_u32_e32 v12, 0, v212
	s_cmp_lg_u32 0, -1
	s_waitcnt vmcnt(1)
	ds_write_b128 v12, v[184:187] offset:32768
	v_lshlrev_b32_e32 v12, 8, v50
	v_bitop3_b32 v213, v12, v4, v2 bitop3:0xf6
	v_and_b32_e32 v5, 24, v3
	v_add_u32_e32 v2, 0, v213
	s_cselect_b32 s4, 0, 0
	s_lshl_b32 s8, s23, 8
	v_and_b32_e32 v3, 0x100, v3
	s_waitcnt vmcnt(0)
; __device__ __forceinline__ int v_st(int k, int c) { const int kk = (k & ~0xC) | ((k & 4) << 1) | ((k & 8) >> 1); return ((kk >> 3) * 4 + (c >> 5)) * 512 + ((kk & 7) * 32 + (c & 31)) * 2; }
; __device__ __forceinline__ int v_rd_base(int lane) { return ((lane & 3) << 3) | (((lane >> 2) & 3) << 6) | (((lane >> 4) & 1) << 5) | (((lane >> 5) & 1) << 8); }
; #define SLOAD2(k0) do { vs0 = *reinterpret_cast<const bf16x8*>(&Vh[(long)((k0) + sr) * ldv + sc]); vs1 = *reinterpret_cast<const bf16x8*>(&Vh[(long)((k0) + 32 + sr) * ldv + sc]); \
;     ks0 = *reinterpret_cast<const bf16x8*>(&Kh[(long)((k0) + sr) * ldk + sc]); ks1 = *reinterpret_cast<const bf16x8*>(&Kh[(long)((k0) + 32 + sr) * ldk + sc]); } while (0)
; #define SWRITE2(b) do { *(bf16x8*)(V_lds + (b) * SHM_V + vst0) = vs0; *(bf16x8*)(V_lds + (b) * SHM_V + vst1) = vs1; \
;     *(bf16x8*)(K_lds + (b) * SHM_K + KSWZ(sr, sc * 2)) = ks0; *(bf16x8*)(K_lds + (b) * SHM_K + KSWZ(32 + sr, sc * 2)) = ks1; } while (0)
; __device__ __forceinline__ void attn_unit_A2(const bf16_t* __restrict__ Qb, int ldq, const bf16_t* __restrict__ Kh, int ldk, const bf16_t* __restrict__ Vh, int ldv, int nkeys, int q0, ...
;     ...
;   float m0 = -1e30f, m1 = -1e30f, l0 = 0.f, l1 = 0.f; f32x16 oa[4] = {}, ob[4] = {};
;   const int sr = tid >> 4, sc = (tid & 15) * 8, vst0 = v_st(sr, sc), vst1 = v_st(32 + sr, sc);
;   const int vb0 = (int)(uintptr_t)V_lds + v_rd_base(lane);
;   const int qlane = q0 + wid * QBLK + r32;
;   bf16x8 vs0, vs1, ks0, ks1;
;     ...
;   const int NT = nkeys / KVBLK;
;   const int kbA = (int)(uintptr_t)K_lds + r32 * 256 + (((r32 & 15) << 4) ^ (hi << 4)), qaA = (int)(uintptr_t)qls;
;   SLOAD2(0); asm volatile("s_waitcnt vmcnt(0)" ::: "memory"); SWRITE2(0); __syncthreads();
	ds_write_b128 v2, v[188:191] offset:32768
	v_add3_u32 v2, v8, s4, v5
	s_add_i32 s7, s7, s8
	v_add3_u32 v214, v2, v10, v3
	v_add_u32_e32 v2, s7, v196
	v_or_b32_e32 v2, v2, v46
	v_lshlrev_b32_e32 v2, 2, v2
	v_add_u32_e32 v216, v201, v0
	v_sub_u32_e32 v0, v0, v2
	v_add_u32_e32 v217, 0, v0
	v_lshlrev_b32_e32 v0, 4, v11
	v_or3_b32 v6, v6, s6, v0
	v_mov_b32_e32 v14, v1
	v_mov_b32_e32 v15, v1
	v_cmp_gt_u32_e64 s[4:5], 32, v9
	v_lshl_add_u32 v215, v46, 2, v201
	v_lshl_add_u64 v[198:199], s[18:19], 0, v[6:7]
	v_mov_b32_e32 v0, v1
	v_mov_b32_e32 v2, v1
	v_mov_b32_e32 v3, v1
	v_mov_b32_e32 v4, v1
	v_mov_b32_e32 v5, v1
	v_mov_b32_e32 v6, v1
	v_mov_b32_e32 v7, v1
	v_mov_b32_e32 v8, v1
	v_mov_b32_e32 v9, v1
	v_mov_b32_e32 v10, v1
	v_mov_b32_e32 v11, v1
	v_mov_b32_e32 v12, v1
	v_mov_b32_e32 v13, v1
	v_mov_b64_e32 v[46:47], v[14:15]
	v_mov_b64_e32 v[30:31], v[14:15]
	v_mov_b64_e32 v[78:79], v[14:15]
	v_mov_b64_e32 v[126:127], v[14:15]
	v_mov_b64_e32 v[142:143], v[14:15]
	v_mov_b64_e32 v[110:111], v[14:15]
	v_mov_b64_e32 v[62:63], v[14:15]
	v_mov_b64_e32 v[94:95], v[14:15]
	s_mov_b32 s11, 0
	s_sub_i32 s61, 0, s7
	v_mov_b32_e32 v218, 0xc3480000
	v_mov_b32_e32 v219, 0
	s_mov_b32 s62, 0
	s_mov_b32 s63, 0
	v_mov_b64_e32 v[44:45], v[12:13]
	v_mov_b64_e32 v[42:43], v[10:11]
	v_mov_b64_e32 v[40:41], v[8:9]
	v_mov_b64_e32 v[38:39], v[6:7]
	v_mov_b64_e32 v[36:37], v[4:5]
	v_mov_b64_e32 v[34:35], v[2:3]
	v_mov_b64_e32 v[32:33], v[0:1]
	v_mov_b64_e32 v[28:29], v[12:13]
	v_mov_b64_e32 v[26:27], v[10:11]
	v_mov_b64_e32 v[24:25], v[8:9]
	v_mov_b64_e32 v[22:23], v[6:7]
	v_mov_b64_e32 v[20:21], v[4:5]
	v_mov_b64_e32 v[18:19], v[2:3]
	v_mov_b64_e32 v[16:17], v[0:1]
	v_mov_b64_e32 v[76:77], v[12:13]
	v_mov_b64_e32 v[74:75], v[10:11]
	v_mov_b64_e32 v[72:73], v[8:9]
	v_mov_b64_e32 v[70:71], v[6:7]
	v_mov_b64_e32 v[68:69], v[4:5]
	v_mov_b64_e32 v[66:67], v[2:3]
	v_mov_b64_e32 v[64:65], v[0:1]
	v_mov_b64_e32 v[124:125], v[12:13]
	v_mov_b64_e32 v[122:123], v[10:11]
	v_mov_b64_e32 v[120:121], v[8:9]
	v_mov_b64_e32 v[118:119], v[6:7]
	v_mov_b64_e32 v[116:117], v[4:5]
	v_mov_b64_e32 v[114:115], v[2:3]
	v_mov_b64_e32 v[112:113], v[0:1]
	v_mov_b64_e32 v[140:141], v[12:13]
	v_mov_b64_e32 v[138:139], v[10:11]
	v_mov_b64_e32 v[136:137], v[8:9]
	v_mov_b64_e32 v[134:135], v[6:7]
	v_mov_b64_e32 v[132:133], v[4:5]
	v_mov_b64_e32 v[130:131], v[2:3]
	v_mov_b64_e32 v[128:129], v[0:1]
	v_mov_b64_e32 v[108:109], v[12:13]
	v_mov_b64_e32 v[106:107], v[10:11]
	v_mov_b64_e32 v[104:105], v[8:9]
	v_mov_b64_e32 v[102:103], v[6:7]
	v_mov_b64_e32 v[100:101], v[4:5]
	v_mov_b64_e32 v[98:99], v[2:3]
	v_mov_b64_e32 v[96:97], v[0:1]
	v_mov_b64_e32 v[60:61], v[12:13]
	v_mov_b64_e32 v[58:59], v[10:11]
	v_mov_b64_e32 v[56:57], v[8:9]
	v_mov_b64_e32 v[54:55], v[6:7]
	v_mov_b64_e32 v[52:53], v[4:5]
	v_mov_b64_e32 v[50:51], v[2:3]
	v_mov_b64_e32 v[48:49], v[0:1]
	v_mov_b64_e32 v[92:93], v[12:13]
	v_mov_b64_e32 v[90:91], v[10:11]
	v_mov_b64_e32 v[88:89], v[8:9]
	v_mov_b64_e32 v[86:87], v[6:7]
	v_mov_b64_e32 v[84:85], v[4:5]
	v_mov_b64_e32 v[82:83], v[2:3]
	v_mov_b64_e32 v[80:81], v[0:1]
	v_mov_b32_e32 v14, 0
	v_mov_b32_e32 v0, 0xc3480000
	v_mbcnt_lo_u32_b32 v184, -1, 0
	v_mbcnt_hi_u32_b32 v184, -1, v184
	v_readlane_b32 s6, v254, 8
	s_nop 1
	v_add_u32_e32 v184, s6, v184
	v_lshrrev_b32_e32 v185, 4, v184
	v_and_b32_e32 v186, 15, v184
	v_and_b32_e32 v187, 15, v185
	v_xor_b32_e32 v187, v186, v187
	v_sub_u32_e32 v187, v187, v186
	v_lshlrev_b32_e32 v187, 4, v187
	v_add_u32_e32 v187, 0xfffafc00, v187
	v_add_co_u32_e32 v180, vcc, v187, v198
	s_nop 1
	v_addc_co_u32_e32 v181, vcc, -1, v199, vcc
	v_add_co_u32_e32 v182, vcc, 0x50000, v180
	s_nop 1
	v_addc_co_u32_e32 v183, vcc, 0, v181, vcc
	v_lshrrev_b32_e32 v187, 7, v184
	v_lshlrev_b32_e32 v187, 3, v187
	v_bfe_u32 v188, v184, 2, 3
	v_add_u32_e32 v187, v187, v188
	v_sub_u32_e32 v187, v187, v185
	v_mul_i32_i24_e32 v187, 0x2800, v187
	v_bfe_u32 v188, v184, 5, 2
	v_lshlrev_b32_e32 v188, 6, v188
	v_and_b32_e32 v189, 3, v184
	v_lshl_add_u32 v188, v189, 4, v188
	v_lshlrev_b32_e32 v186, 4, v186
	v_sub_u32_e32 v188, v188, v186
	v_add_u32_e32 v187, v187, v188
	v_add_u32_e32 v187, 0xfffb0000, v187
	v_add_co_u32_e32 v176, vcc, v187, v198
	s_nop 1
	v_addc_co_u32_e32 v177, vcc, -1, v199, vcc
	v_add_co_u32_e32 v178, vcc, 0x50000, v176
	s_nop 1
	v_addc_co_u32_e32 v179, vcc, 0, v177, vcc
	s_waitcnt lgkmcnt(0)
	s_barrier

; __device__ __forceinline__ void pv_d0(f32x16* o, int vb, bf16x8 pa0, bf16x8 pa1, bf16x8 pa2, bf16x8 pa3) {
;     ...
;   const s16x4 l0 = tr_read<v_rd_off(0, 0, 0)>(vb), h0 = tr_read<v_rd_off(0, 0, 1)>(vb);
;   const s16x4 l1 = tr_read<v_rd_off(0, 1, 0)>(vb), h1 = tr_read<v_rd_off(0, 1, 1)>(vb);
;   const s16x4 l2 = tr_read<v_rd_off(0, 2, 0)>(vb), h2 = tr_read<v_rd_off(0, 2, 1)>(vb);
;   const s16x4 l3 = tr_read<v_rd_off(0, 3, 0)>(vb), h3 = tr_read<v_rd_off(0, 3, 1)>(vb);
;   const s16x4 l4 = tr_read<v_rd_off(1, 0, 0)>(vb), h4 = tr_read<v_rd_off(1, 0, 1)>(vb);
;   asm volatile("s_waitcnt lgkmcnt(8)" ::: "memory"); SBAR();
;   o[0] = __builtin_amdgcn_mfma_f32_32x32x16_bf16(pa0, PK(l0, h0), o[0], 0, 0, 0);
;   const s16x4 l5 = tr_read<v_rd_off(1, 1, 0)>(vb), h5 = tr_read<v_rd_off(1, 1, 1)>(vb);
;   asm volatile("s_waitcnt lgkmcnt(8)" ::: "memory"); SBAR();
;   o[0] = __builtin_amdgcn_mfma_f32_32x32x16_bf16(pa1, PK(l1, h1), o[0], 0, 0, 0);
;   const s16x4 l6 = tr_read<v_rd_off(1, 2, 0)>(vb), h6 = tr_read<v_rd_off(1, 2, 1)>(vb);
;   asm volatile("s_waitcnt lgkmcnt(8)" ::: "memory"); SBAR();
;   o[0] = __builtin_amdgcn_mfma_f32_32x32x16_bf16(pa2, PK(l2, h2), o[0], 0, 0, 0);
;   const s16x4 l7 = tr_read<v_rd_off(1, 3, 0)>(vb), h7 = tr_read<v_rd_off(1, 3, 1)>(vb);
;   asm volatile("s_waitcnt lgkmcnt(8)" ::: "memory"); SBAR();
;   o[0] = __builtin_amdgcn_mfma_f32_32x32x16_bf16(pa3, PK(l3, h3), o[0], 0, 0, 0);
;   const s16x4 l8 = tr_read<v_rd_off(2, 0, 0)>(vb), h8 = tr_read<v_rd_off(2, 0, 1)>(vb);
;   asm volatile("s_waitcnt lgkmcnt(8)" ::: "memory"); SBAR();
;   o[1] = __builtin_amdgcn_mfma_f32_32x32x16_bf16(pa0, PK(l4, h4), o[1], 0, 0, 0);
;   const s16x4 l9 = tr_read<v_rd_off(2, 1, 0)>(vb), h9 = tr_read<v_rd_off(2, 1, 1)>(vb);
;   asm volatile("s_waitcnt lgkmcnt(8)" ::: "memory"); SBAR();
;   o[1] = __builtin_amdgcn_mfma_f32_32x32x16_bf16(pa1, PK(l5, h5), o[1], 0, 0, 0);
;   const s16x4 l10 = tr_read<v_rd_off(2, 2, 0)>(vb), h10 = tr_read<v_rd_off(2, 2, 1)>(vb);
;   asm volatile("s_waitcnt lgkmcnt(8)" ::: "memory"); SBAR();
;   o[1] = __builtin_amdgcn_mfma_f32_32x32x16_bf16(pa2, PK(l6, h6), o[1], 0, 0, 0);
;   const s16x4 l11 = tr_read<v_rd_off(2, 3, 0)>(vb), h11 = tr_read<v_rd_off(2, 3, 1)>(vb);
;   asm volatile("s_waitcnt lgkmcnt(8)" ::: "memory"); SBAR();
;   o[1] = __builtin_amdgcn_mfma_f32_32x32x16_bf16(pa3, PK(l7, h7), o[1], 0, 0, 0);
.LBB0_347:
	s_cmpk_eq_u32 s63, 0xff00
	s_cbranch_scc1 .LBB0_349
	v_readlane_b32 s6, v254, 8
	s_xor_b32 s7, s64, 0x4000
	s_nop 0
	s_lshl_b32 s6, s6, 4
	s_add_i32 s6, s6, s7
	s_mov_b32 m0, s6
	s_nop 0
	global_load_lds_dwordx4 v[176:177], off
	s_add_i32 m0, s6, 0x2000
	s_nop 0
	global_load_lds_dwordx4 v[178:179], off
	s_add_i32 m0, s6, 0x8000
	s_nop 0
	global_load_lds_dwordx4 v[180:181], off
	s_add_i32 m0, s6, 0xa000
	s_nop 0
	global_load_lds_dwordx4 v[182:183], off
	v_lshl_add_u64 v[176:177], v[176:177], 0, s[92:93]
	v_lshl_add_u64 v[178:179], v[178:179], 0, s[92:93]
	v_lshl_add_u64 v[180:181], v[180:181], 0, s[92:93]
	v_lshl_add_u64 v[182:183], v[182:183], 0, s[92:93]
.LBB0_349:
	ds_read_b64_tr_b16 v[150:151], v222 offset:0
	ds_read_b64_tr_b16 v[152:153], v222 offset:0x800
	ds_read_b64_tr_b16 v[154:155], v222 offset:0x1000
	ds_read_b64_tr_b16 v[156:157], v222 offset:0x1800
	ds_read_b64_tr_b16 v[158:159], v222 offset:0x2000
	ds_read_b64_tr_b16 v[160:161], v222 offset:0x2800
	ds_read_b64_tr_b16 v[162:163], v222 offset:0x3000
	ds_read_b64_tr_b16 v[164:165], v222 offset:0x3800
	ds_read_b64_tr_b16 v[166:167], v222 offset:0x200
	ds_read_b64_tr_b16 v[168:169], v222 offset:0xa00
	s_waitcnt lgkmcnt(8)
	s_nop 0
	v_mfma_f32_32x32x16_bf16 v[112:127], v[2:5], v[150:153], v[112:127]
	ds_read_b64_tr_b16 v[150:151], v222 offset:0x1200
	ds_read_b64_tr_b16 v[152:153], v222 offset:0x1a00
	s_waitcnt lgkmcnt(8)
	v_mfma_f32_32x32x16_bf16 v[112:127], v[6:9], v[154:157], v[112:127]
	ds_read_b64_tr_b16 v[154:155], v222 offset:0x2200
	ds_read_b64_tr_b16 v[156:157], v222 offset:0x2a00
	s_waitcnt lgkmcnt(8)
	v_mfma_f32_32x32x16_bf16 v[112:127], v[10:13], v[158:161], v[112:127]
	ds_read_b64_tr_b16 v[158:159], v222 offset:0x3200
	ds_read_b64_tr_b16 v[160:161], v222 offset:0x3a00
	s_waitcnt lgkmcnt(8)
	v_mfma_f32_32x32x16_bf16 v[112:127], v[144:147], v[162:165], v[112:127]
	ds_read_b64_tr_b16 v[162:163], v222 offset:0x400
	ds_read_b64_tr_b16 v[164:165], v222 offset:0xc00
	s_waitcnt lgkmcnt(8)
	v_mfma_f32_32x32x16_bf16 v[64:79], v[2:5], v[166:169], v[64:79]
	ds_read_b64_tr_b16 v[166:167], v222 offset:0x1400
	ds_read_b64_tr_b16 v[168:169], v222 offset:0x1c00
	s_waitcnt lgkmcnt(8)
	v_mfma_f32_32x32x16_bf16 v[64:79], v[6:9], v[150:153], v[64:79]
	ds_read_b64_tr_b16 v[150:151], v222 offset:0x2400
	ds_read_b64_tr_b16 v[152:153], v222 offset:0x2c00
	s_waitcnt lgkmcnt(8)
	v_mfma_f32_32x32x16_bf16 v[64:79], v[10:13], v[154:157], v[64:79]
	ds_read_b64_tr_b16 v[154:155], v222 offset:0x3400
	ds_read_b64_tr_b16 v[156:157], v222 offset:0x3c00
	s_waitcnt lgkmcnt(8)
	v_mfma_f32_32x32x16_bf16 v[64:79], v[144:147], v[158:161], v[64:79]
	ds_read_b64_tr_b16 v[158:159], v222 offset:0x600
	ds_read_b64_tr_b16 v[160:161], v222 offset:0xe00
	s_waitcnt lgkmcnt(8)
	v_mfma_f32_32x32x16_bf16 v[16:31], v[2:5], v[162:165], v[16:31]
	ds_read_b64_tr_b16 v[162:163], v222 offset:0x1600
	ds_read_b64_tr_b16 v[164:165], v222 offset:0x1e00
	s_waitcnt lgkmcnt(8)
	v_mfma_f32_32x32x16_bf16 v[16:31], v[6:9], v[166:169], v[16:31]
	ds_read_b64_tr_b16 v[166:167], v222 offset:0x2600
	ds_read_b64_tr_b16 v[168:169], v222 offset:0x2e00
	s_waitcnt lgkmcnt(8)
	v_mfma_f32_32x32x16_bf16 v[16:31], v[10:13], v[150:153], v[16:31]
	ds_read_b64_tr_b16 v[150:151], v222 offset:0x3600
	ds_read_b64_tr_b16 v[152:153], v222 offset:0x3e00
	s_waitcnt lgkmcnt(8)
	v_mfma_f32_32x32x16_bf16 v[16:31], v[144:147], v[154:157], v[16:31]
	s_waitcnt lgkmcnt(6)
	v_mfma_f32_32x32x16_bf16 v[32:47], v[2:5], v[158:161], v[32:47]
	s_waitcnt lgkmcnt(4)
	v_mfma_f32_32x32x16_bf16 v[32:47], v[6:9], v[162:165], v[32:47]
	s_waitcnt lgkmcnt(2)
	v_mfma_f32_32x32x16_bf16 v[32:47], v[10:13], v[166:169], v[32:47]
	s_waitcnt lgkmcnt(0)
	v_mfma_f32_32x32x16_bf16 v[32:47], v[144:147], v[150:153], v[32:47]
	s_waitcnt vmcnt(0)
